# FFN1 K-loop: LDS-DMA issue rebalanced 4/4/4/4 across the four phases, vmcnt waits re-derived (8/6/8/6)
# baseline (speedup 1.0000x reference)
; #define PG8_STAGE(bufoff, gbase, voff) do { _Pragma("unroll") for (int _i = 0; _i < 2; ++_i) \
;         __builtin_amdgcn_global_load_lds((const unsigned*)((const char*)(gbase) + (voff)[_i]), (LAS unsigned*)(lds + (bufoff) + ldsw + _i * 8192), 16, 0, 0); } while (0)
; #define PG8_WAIT_V(n) asm volatile("s_waitcnt vmcnt(" #n ")" ::: "memory")
; #define PG8_WAIT_L(n) asm volatile("s_waitcnt lgkmcnt(" #n ")" ::: "memory")
; #define PG8_BAR __builtin_amdgcn_s_barrier()
; #define PG8_SCHED __builtin_amdgcn_sched_barrier(0)
; template <bool F8 = false, class Epi, class Sched>
; __device__ __forceinline__ void gemm_phase(LAS unsigned char* lds, const int lda, const int ldb, const int K, const Sched& S, const Epi& E) {
;     ...
;         for (int t = 0; t < nt; t += 2) {
;             const bool last = (t == nt - 2);
;             const char* a1 = cA + (size_t)(t + 1) * kstep;
;             const char* a2 = last ? nA : cA + (size_t)(t + 2) * kstep; const char* b2 = last ? nB : cB + (size_t)(t + 2) * kstep;
;             const char* a3 = a2 + kstep; const char* b3 = b2 + kstep;
;             PG8_LDB(B0, 0, 0); PG8_LDB(B1, 0, 1); PG8_SCHED; PG8_LDA(At, 0, 0); PG8_STAGE(PG8_SA(1, 1), a1 + hstepA, voffA);
;             PG8_WAIT_V(8); PG8_WAIT_L(0); PG8_BAR; PG8_MMA(0, 0, At, B0); PG8_MMA(0, 1, At, B1); PG8_BAR; PG8_SCHED;
;             PG8_LDA(At, 0, 1); PG8_STAGE(PG8_SB(0, 0), b2, voffB); PG8_STAGE(PG8_SB(0, 1), b2 + hstepB, voffB); PG8_STAGE(PG8_SA(0, 0), a2, voffA);
;             PG8_WAIT_V(8); PG8_WAIT_L(0); PG8_BAR; PG8_MMA(1, 0, At, B0); PG8_MMA(1, 1, At, B1); PG8_BAR; PG8_SCHED;
.LBB0_1062:
	s_add_u32 s30, vcc_lo, 0xfff80080
	s_addc_u32 s31, vcc_hi, -1
	s_add_i32 s33, 0, 0x10000
	s_cmp_eq_u32 s29, 28
	s_cselect_b32 s75, s13, s31
	s_cselect_b32 s74, s26, s30
	s_cselect_b32 s53, s9, s28
	s_cselect_b32 s52, s27, s73
	s_add_i32 s93, 0, 0x14000
	v_add_u32_e32 v152, s33, v141
	v_add_u32_e32 v168, s93, v141
	ds_read_b128 v[136:139], v152
	ds_read_b128 v[144:147], v152 offset:1024
	ds_read_b128 v[148:151], v152 offset:2048
	ds_read_b128 v[152:155], v152 offset:3072
	ds_read_b128 v[156:159], v168
	ds_read_b128 v[160:163], v168 offset:1024
	ds_read_b128 v[164:167], v168 offset:2048
	ds_read_b128 v[168:171], v168 offset:3072
	s_add_u32 s30, s73, 0x7ff80
	s_addc_u32 s31, s28, 0
	s_add_i32 m0, s94, 0x1c000
	v_lshl_add_u64 v[210:211], s[30:31], 0, v[0:1]
	global_load_lds_dwordx4 v[210:211], off
	s_add_i32 m0, s94, 0x1e000
	v_lshl_add_u64 v[210:211], s[30:31], 0, v[130:131]
	global_load_lds_dwordx4 v[210:211], off
	v_lshl_add_u64 v[210:211], vcc, 0, v[132:133]
	s_add_i32 m0, s19, 0xc000
	ds_read_b128 v[172:175], v143
	ds_read_b128 v[176:179], v143 offset:1024
	ds_read_b128 v[180:183], v143 offset:2048
	ds_read_b128 v[184:187], v143 offset:3072
	ds_read_b128 v[188:191], v143 offset:4096
	ds_read_b128 v[192:195], v143 offset:5120
	ds_read_b128 v[202:205], v143 offset:6144
	ds_read_b128 v[206:209], v143 offset:7168
	global_load_lds_dwordx4 v[210:211], off
	v_lshl_add_u64 v[210:211], vcc, 0, v[134:135]
	s_add_i32 m0, s19, 0xe000
	s_nop 0
	global_load_lds_dwordx4 v[210:211], off
	s_waitcnt vmcnt(8)
	s_waitcnt lgkmcnt(0)
	s_barrier
	s_setprio 1
	s_waitcnt lgkmcnt(0)
	v_mfma_f32_16x16x32_bf16 v[126:129], v[136:139], v[172:175], v[126:129]
	v_mfma_f32_16x16x32_bf16 v[122:125], v[148:151], v[172:175], v[122:125]
	v_mfma_f32_16x16x32_bf16 v[110:113], v[136:139], v[180:183], v[110:113]
	v_mfma_f32_16x16x32_bf16 v[106:109], v[148:151], v[180:183], v[106:109]
	v_mfma_f32_16x16x32_bf16 v[94:97], v[136:139], v[188:191], v[94:97]
	v_mfma_f32_16x16x32_bf16 v[90:93], v[148:151], v[188:191], v[90:93]
	v_mfma_f32_16x16x32_bf16 v[78:81], v[136:139], v[202:205], v[78:81]
	v_mfma_f32_16x16x32_bf16 v[74:77], v[148:151], v[202:205], v[74:77]
	v_mfma_f32_16x16x32_bf16 v[126:129], v[144:147], v[176:179], v[126:129]
	v_mfma_f32_16x16x32_bf16 v[122:125], v[152:155], v[176:179], v[122:125]
	v_mfma_f32_16x16x32_bf16 v[110:113], v[144:147], v[184:187], v[110:113]
	v_mfma_f32_16x16x32_bf16 v[106:109], v[152:155], v[184:187], v[106:109]
	v_mfma_f32_16x16x32_bf16 v[94:97], v[144:147], v[192:195], v[94:97]
	v_mfma_f32_16x16x32_bf16 v[90:93], v[152:155], v[192:195], v[90:93]
	v_mfma_f32_16x16x32_bf16 v[78:81], v[144:147], v[206:209], v[78:81]
	v_mfma_f32_16x16x32_bf16 v[74:77], v[152:155], v[206:209], v[74:77]
	s_setprio 0
	s_setprio 1
	v_mfma_f32_16x16x32_bf16 v[118:121], v[156:159], v[172:175], v[118:121]
	v_mfma_f32_16x16x32_bf16 v[114:117], v[164:167], v[172:175], v[114:117]
	v_mfma_f32_16x16x32_bf16 v[102:105], v[156:159], v[180:183], v[102:105]
	v_mfma_f32_16x16x32_bf16 v[98:101], v[164:167], v[180:183], v[98:101]
	v_mfma_f32_16x16x32_bf16 v[86:89], v[156:159], v[188:191], v[86:89]
	v_mfma_f32_16x16x32_bf16 v[82:85], v[164:167], v[188:191], v[82:85]
	v_mfma_f32_16x16x32_bf16 v[70:73], v[156:159], v[202:205], v[70:73]
	v_mfma_f32_16x16x32_bf16 v[66:69], v[164:167], v[202:205], v[66:69]
	v_mfma_f32_16x16x32_bf16 v[118:121], v[160:163], v[176:179], v[118:121]
	v_mfma_f32_16x16x32_bf16 v[114:117], v[168:171], v[176:179], v[114:117]
	v_mfma_f32_16x16x32_bf16 v[102:105], v[160:163], v[184:187], v[102:105]
	v_mfma_f32_16x16x32_bf16 v[98:101], v[168:171], v[184:187], v[98:101]
	v_mfma_f32_16x16x32_bf16 v[86:89], v[160:163], v[192:195], v[86:89]
	v_mfma_f32_16x16x32_bf16 v[82:85], v[168:171], v[192:195], v[82:85]
	v_mfma_f32_16x16x32_bf16 v[70:73], v[160:163], v[206:209], v[70:73]
	v_mfma_f32_16x16x32_bf16 v[66:69], v[168:171], v[206:209], v[66:69]
	s_setprio 0
	s_barrier
	s_add_i32 s30, s33, s94
	v_lshl_add_u64 v[210:211], s[52:53], 0, v[0:1]
	s_mov_b32 m0, s30
	ds_read_b128 v[172:175], v143 offset:16384
	ds_read_b128 v[176:179], v143 offset:17408
	ds_read_b128 v[180:183], v143 offset:18432
	ds_read_b128 v[184:187], v143 offset:19456
	ds_read_b128 v[188:191], v143 offset:20480
	ds_read_b128 v[192:195], v143 offset:21504
	ds_read_b128 v[202:205], v143 offset:22528
	ds_read_b128 v[206:209], v143 offset:23552
	global_load_lds_dwordx4 v[210:211], off
	s_add_i32 m0, s30, 0x2000
	s_add_u32 s30, s52, 0x80000
	v_lshl_add_u64 v[212:213], s[52:53], 0, v[130:131]
	s_addc_u32 s31, s53, 0
	s_add_i32 s33, s93, s94
	global_load_lds_dwordx4 v[212:213], off
	v_lshl_add_u64 v[216:217], s[74:75], 0, v[130:131]
	v_lshl_add_u64 v[214:215], s[74:75], 0, v[0:1]
	s_mov_b32 m0, s19
	s_nop 0
	global_load_lds_dwordx4 v[214:215], off
	s_mov_b32 m0, s56
	s_nop 0
	global_load_lds_dwordx4 v[216:217], off
	s_waitcnt vmcnt(6)
	s_waitcnt lgkmcnt(0)
	s_barrier
; #define PG8_STAGE(bufoff, gbase, voff) do { _Pragma("unroll") for (int _i = 0; _i < 2; ++_i) \
;         __builtin_amdgcn_global_load_lds((const unsigned*)((const char*)(gbase) + (voff)[_i]), (LAS unsigned*)(lds + (bufoff) + ldsw + _i * 8192), 16, 0, 0); } while (0)
; #define PG8_WAIT_V(n) asm volatile("s_waitcnt vmcnt(" #n ")" ::: "memory")
; #define PG8_WAIT_L(n) asm volatile("s_waitcnt lgkmcnt(" #n ")" ::: "memory")
; #define PG8_BAR __builtin_amdgcn_s_barrier()
; #define PG8_SCHED __builtin_amdgcn_sched_barrier(0)
; template <bool F8 = false, class Epi, class Sched>
; __device__ __forceinline__ void gemm_phase(LAS unsigned char* lds, const int lda, const int ldb, const int K, const Sched& S, const Epi& E) {
;     ...
;             PG8_WAIT_V(8); PG8_WAIT_L(0); PG8_BAR; PG8_MMA(1, 0, At, B0); PG8_MMA(1, 1, At, B1); PG8_BAR; PG8_SCHED;
;             PG8_LDB(B0, 1, 0); PG8_LDB(B1, 1, 1); PG8_SCHED; PG8_LDA(At, 1, 0); PG8_STAGE(PG8_SA(0, 1), a2 + hstepA, voffA);
;             PG8_WAIT_V(8); PG8_WAIT_L(0); PG8_BAR; PG8_MMA(0, 0, At, B0); PG8_MMA(0, 1, At, B1); PG8_BAR; PG8_SCHED;
;             PG8_LDA(At, 1, 1); PG8_STAGE(PG8_SB(1, 0), b3, voffB); PG8_STAGE(PG8_SB(1, 1), b3 + hstepB, voffB); PG8_STAGE(PG8_SA(1, 0), a3, voffA);
	s_setprio 1
	s_waitcnt lgkmcnt(0)
	v_mfma_f32_16x16x32_bf16 v[62:65], v[136:139], v[172:175], v[62:65]
	v_mfma_f32_16x16x32_bf16 v[58:61], v[148:151], v[172:175], v[58:61]
	v_mfma_f32_16x16x32_bf16 v[46:49], v[136:139], v[180:183], v[46:49]
	v_mfma_f32_16x16x32_bf16 v[42:45], v[148:151], v[180:183], v[42:45]
	v_mfma_f32_16x16x32_bf16 v[30:33], v[136:139], v[188:191], v[30:33]
	v_mfma_f32_16x16x32_bf16 v[26:29], v[148:151], v[188:191], v[26:29]
	v_mfma_f32_16x16x32_bf16 v[14:17], v[136:139], v[202:205], v[14:17]
	v_mfma_f32_16x16x32_bf16 v[10:13], v[148:151], v[202:205], v[10:13]
	v_mfma_f32_16x16x32_bf16 v[62:65], v[144:147], v[176:179], v[62:65]
	v_mfma_f32_16x16x32_bf16 v[58:61], v[152:155], v[176:179], v[58:61]
	v_mfma_f32_16x16x32_bf16 v[46:49], v[144:147], v[184:187], v[46:49]
	v_mfma_f32_16x16x32_bf16 v[42:45], v[152:155], v[184:187], v[42:45]
	v_mfma_f32_16x16x32_bf16 v[30:33], v[144:147], v[192:195], v[30:33]
	v_mfma_f32_16x16x32_bf16 v[26:29], v[152:155], v[192:195], v[26:29]
	v_mfma_f32_16x16x32_bf16 v[14:17], v[144:147], v[206:209], v[14:17]
	v_mfma_f32_16x16x32_bf16 v[10:13], v[152:155], v[206:209], v[10:13]
	s_setprio 0
	s_setprio 1
	v_mfma_f32_16x16x32_bf16 v[54:57], v[156:159], v[172:175], v[54:57]
	v_mfma_f32_16x16x32_bf16 v[50:53], v[164:167], v[172:175], v[50:53]
	v_mfma_f32_16x16x32_bf16 v[38:41], v[156:159], v[180:183], v[38:41]
	v_mfma_f32_16x16x32_bf16 v[34:37], v[164:167], v[180:183], v[34:37]
	v_mfma_f32_16x16x32_bf16 v[22:25], v[156:159], v[188:191], v[22:25]
	v_mfma_f32_16x16x32_bf16 v[18:21], v[164:167], v[188:191], v[18:21]
	v_mfma_f32_16x16x32_bf16 v[6:9], v[156:159], v[202:205], v[6:9]
	v_mfma_f32_16x16x32_bf16 v[2:5], v[164:167], v[202:205], v[2:5]
	v_mfma_f32_16x16x32_bf16 v[54:57], v[160:163], v[176:179], v[54:57]
	v_mfma_f32_16x16x32_bf16 v[50:53], v[168:171], v[176:179], v[50:53]
	v_mfma_f32_16x16x32_bf16 v[38:41], v[160:163], v[184:187], v[38:41]
	v_mfma_f32_16x16x32_bf16 v[34:37], v[168:171], v[184:187], v[34:37]
	v_mfma_f32_16x16x32_bf16 v[22:25], v[160:163], v[192:195], v[22:25]
	v_mfma_f32_16x16x32_bf16 v[18:21], v[168:171], v[192:195], v[18:21]
	v_mfma_f32_16x16x32_bf16 v[6:9], v[160:163], v[206:209], v[6:9]
	v_mfma_f32_16x16x32_bf16 v[2:5], v[168:171], v[206:209], v[2:5]
	s_setprio 0
	s_barrier
	s_add_i32 s33, 0, 0x18000
	s_add_i32 s93, 0, 0x1c000
	v_add_u32_e32 v152, s33, v141
	v_add_u32_e32 v168, s93, v141
	ds_read_b128 v[136:139], v152
	ds_read_b128 v[144:147], v152 offset:1024
	ds_read_b128 v[148:151], v152 offset:2048
	ds_read_b128 v[152:155], v152 offset:3072
	ds_read_b128 v[156:159], v168
	ds_read_b128 v[160:163], v168 offset:1024
	ds_read_b128 v[164:167], v168 offset:2048
	ds_read_b128 v[168:171], v168 offset:3072
	s_add_u32 s30, s52, 0x80000
	s_addc_u32 s31, s53, 0
	s_add_i32 m0, s94, 0x14000
	v_lshl_add_u64 v[218:219], s[30:31], 0, v[0:1]
	global_load_lds_dwordx4 v[218:219], off
	s_add_i32 m0, s94, 0x16000
	v_lshl_add_u64 v[218:219], s[30:31], 0, v[130:131]
	global_load_lds_dwordx4 v[218:219], off
	s_add_u32 s30, s74, 0x80000
	s_addc_u32 s31, s75, 0
	s_mov_b32 m0, s57
	v_lshl_add_u64 v[218:219], s[30:31], 0, v[0:1]
	ds_read_b128 v[172:175], v143 offset:32768
	ds_read_b128 v[176:179], v143 offset:33792
	ds_read_b128 v[180:183], v143 offset:34816
	ds_read_b128 v[184:187], v143 offset:35840
	ds_read_b128 v[188:191], v143 offset:36864
	ds_read_b128 v[192:195], v143 offset:37888
	ds_read_b128 v[202:205], v143 offset:38912
	ds_read_b128 v[206:209], v143 offset:39936
	global_load_lds_dwordx4 v[218:219], off
	v_lshl_add_u64 v[218:219], s[30:31], 0, v[130:131]
	s_mov_b32 m0, s96
	s_nop 0
	global_load_lds_dwordx4 v[218:219], off
	s_waitcnt vmcnt(8)
	s_waitcnt lgkmcnt(0)
	s_barrier
; #define PG8_STAGE(bufoff, gbase, voff) do { _Pragma("unroll") for (int _i = 0; _i < 2; ++_i) \
;         __builtin_amdgcn_global_load_lds((const unsigned*)((const char*)(gbase) + (voff)[_i]), (LAS unsigned*)(lds + (bufoff) + ldsw + _i * 8192), 16, 0, 0); } while (0)
; #define PG8_WAIT_V(n) asm volatile("s_waitcnt vmcnt(" #n ")" ::: "memory")
; #define PG8_WAIT_L(n) asm volatile("s_waitcnt lgkmcnt(" #n ")" ::: "memory")
; #define PG8_BAR __builtin_amdgcn_s_barrier()
; #define PG8_SCHED __builtin_amdgcn_sched_barrier(0)
; template <bool F8 = false, class Epi, class Sched>
; __device__ __forceinline__ void gemm_phase(LAS unsigned char* lds, const int lda, const int ldb, const int K, const Sched& S, const Epi& E) {
;     ...
;             PG8_LDB(B0, 1, 0); PG8_LDB(B1, 1, 1); PG8_SCHED; PG8_LDA(At, 1, 0); PG8_STAGE(PG8_SA(0, 1), a2 + hstepA, voffA);
;             PG8_WAIT_V(8); PG8_WAIT_L(0); PG8_BAR; PG8_MMA(0, 0, At, B0); PG8_MMA(0, 1, At, B1); PG8_BAR; PG8_SCHED;
;             PG8_LDA(At, 1, 1); PG8_STAGE(PG8_SB(1, 0), b3, voffB); PG8_STAGE(PG8_SB(1, 1), b3 + hstepB, voffB); PG8_STAGE(PG8_SA(1, 0), a3, voffA);
;             PG8_WAIT_V(8); PG8_WAIT_L(0); PG8_BAR; PG8_MMA(1, 0, At, B0); PG8_MMA(1, 1, At, B1); PG8_BAR; PG8_SCHED;
;         }
;         if (wr == 0) PG8_BAR;
;         E(acc, cur, wr, wc, fr, fq);
;         if (!has_next) break;
	s_setprio 1
	s_waitcnt lgkmcnt(0)
	v_mfma_f32_16x16x32_bf16 v[126:129], v[136:139], v[172:175], v[126:129]
	v_mfma_f32_16x16x32_bf16 v[122:125], v[148:151], v[172:175], v[122:125]
	v_mfma_f32_16x16x32_bf16 v[110:113], v[136:139], v[180:183], v[110:113]
	v_mfma_f32_16x16x32_bf16 v[106:109], v[148:151], v[180:183], v[106:109]
	v_mfma_f32_16x16x32_bf16 v[94:97], v[136:139], v[188:191], v[94:97]
	v_mfma_f32_16x16x32_bf16 v[90:93], v[148:151], v[188:191], v[90:93]
	v_mfma_f32_16x16x32_bf16 v[78:81], v[136:139], v[202:205], v[78:81]
	v_mfma_f32_16x16x32_bf16 v[74:77], v[148:151], v[202:205], v[74:77]
	v_mfma_f32_16x16x32_bf16 v[126:129], v[144:147], v[176:179], v[126:129]
	v_mfma_f32_16x16x32_bf16 v[122:125], v[152:155], v[176:179], v[122:125]
	v_mfma_f32_16x16x32_bf16 v[110:113], v[144:147], v[184:187], v[110:113]
	v_mfma_f32_16x16x32_bf16 v[106:109], v[152:155], v[184:187], v[106:109]
	v_mfma_f32_16x16x32_bf16 v[94:97], v[144:147], v[192:195], v[94:97]
	v_mfma_f32_16x16x32_bf16 v[90:93], v[152:155], v[192:195], v[90:93]
	v_mfma_f32_16x16x32_bf16 v[78:81], v[144:147], v[206:209], v[78:81]
	v_mfma_f32_16x16x32_bf16 v[74:77], v[152:155], v[206:209], v[74:77]
	s_setprio 0
	s_setprio 1
	v_mfma_f32_16x16x32_bf16 v[118:121], v[156:159], v[172:175], v[118:121]
	v_mfma_f32_16x16x32_bf16 v[114:117], v[164:167], v[172:175], v[114:117]
	v_mfma_f32_16x16x32_bf16 v[102:105], v[156:159], v[180:183], v[102:105]
	v_mfma_f32_16x16x32_bf16 v[98:101], v[164:167], v[180:183], v[98:101]
	v_mfma_f32_16x16x32_bf16 v[86:89], v[156:159], v[188:191], v[86:89]
	v_mfma_f32_16x16x32_bf16 v[82:85], v[164:167], v[188:191], v[82:85]
	v_mfma_f32_16x16x32_bf16 v[70:73], v[156:159], v[202:205], v[70:73]
	v_mfma_f32_16x16x32_bf16 v[66:69], v[164:167], v[202:205], v[66:69]
	v_mfma_f32_16x16x32_bf16 v[118:121], v[160:163], v[176:179], v[118:121]
	v_mfma_f32_16x16x32_bf16 v[114:117], v[168:171], v[176:179], v[114:117]
	v_mfma_f32_16x16x32_bf16 v[102:105], v[160:163], v[184:187], v[102:105]
	v_mfma_f32_16x16x32_bf16 v[98:101], v[168:171], v[184:187], v[98:101]
	v_mfma_f32_16x16x32_bf16 v[86:89], v[160:163], v[192:195], v[86:89]
	v_mfma_f32_16x16x32_bf16 v[82:85], v[168:171], v[192:195], v[82:85]
	v_mfma_f32_16x16x32_bf16 v[70:73], v[160:163], v[206:209], v[70:73]
	v_mfma_f32_16x16x32_bf16 v[66:69], v[168:171], v[206:209], v[66:69]
	s_setprio 0
	s_barrier
	s_add_i32 s30, s33, s94
	v_lshl_add_u64 v[210:211], v[210:211], 0, s[40:41]
	s_mov_b32 m0, s30
	ds_read_b128 v[172:175], v143 offset:49152
	ds_read_b128 v[176:179], v143 offset:50176
	ds_read_b128 v[180:183], v143 offset:51200
	ds_read_b128 v[184:187], v143 offset:52224
	ds_read_b128 v[188:191], v143 offset:53248
	ds_read_b128 v[192:195], v143 offset:54272
	ds_read_b128 v[202:205], v143 offset:55296
	ds_read_b128 v[206:209], v143 offset:56320
	global_load_lds_dwordx4 v[210:211], off
	s_add_i32 m0, s30, 0x2000
	s_add_u32 s30, s52, 0x80080
	v_lshl_add_u64 v[210:211], v[212:213], 0, s[40:41]
	s_addc_u32 s31, s53, 0
	s_add_i32 s33, s93, s94
	global_load_lds_dwordx4 v[210:211], off
	v_lshl_add_u64 v[210:211], v[214:215], 0, s[40:41]
	s_mov_b32 m0, s24
	s_nop 0
	global_load_lds_dwordx4 v[210:211], off
	v_lshl_add_u64 v[210:211], v[216:217], 0, s[40:41]
	s_mov_b32 m0, s25
	s_nop 0
	global_load_lds_dwordx4 v[210:211], off
	s_waitcnt vmcnt(6)
	s_waitcnt lgkmcnt(0)
	s_barrier
	s_setprio 1
	s_waitcnt lgkmcnt(0)
	v_mfma_f32_16x16x32_bf16 v[62:65], v[136:139], v[172:175], v[62:65]
	v_mfma_f32_16x16x32_bf16 v[58:61], v[148:151], v[172:175], v[58:61]
	v_mfma_f32_16x16x32_bf16 v[46:49], v[136:139], v[180:183], v[46:49]
	v_mfma_f32_16x16x32_bf16 v[42:45], v[148:151], v[180:183], v[42:45]
	v_mfma_f32_16x16x32_bf16 v[30:33], v[136:139], v[188:191], v[30:33]
	v_mfma_f32_16x16x32_bf16 v[26:29], v[148:151], v[188:191], v[26:29]
	v_mfma_f32_16x16x32_bf16 v[14:17], v[136:139], v[202:205], v[14:17]
	v_mfma_f32_16x16x32_bf16 v[10:13], v[148:151], v[202:205], v[10:13]
	v_mfma_f32_16x16x32_bf16 v[62:65], v[144:147], v[176:179], v[62:65]
	v_mfma_f32_16x16x32_bf16 v[58:61], v[152:155], v[176:179], v[58:61]
	v_mfma_f32_16x16x32_bf16 v[46:49], v[144:147], v[184:187], v[46:49]
	v_mfma_f32_16x16x32_bf16 v[42:45], v[152:155], v[184:187], v[42:45]
	v_mfma_f32_16x16x32_bf16 v[30:33], v[144:147], v[192:195], v[30:33]
	v_mfma_f32_16x16x32_bf16 v[26:29], v[152:155], v[192:195], v[26:29]
	v_mfma_f32_16x16x32_bf16 v[14:17], v[144:147], v[206:209], v[14:17]
	v_mfma_f32_16x16x32_bf16 v[10:13], v[152:155], v[206:209], v[10:13]
	s_setprio 0
	s_setprio 1
	v_mfma_f32_16x16x32_bf16 v[54:57], v[156:159], v[172:175], v[54:57]
	v_mfma_f32_16x16x32_bf16 v[50:53], v[164:167], v[172:175], v[50:53]
	v_mfma_f32_16x16x32_bf16 v[38:41], v[156:159], v[180:183], v[38:41]
	v_mfma_f32_16x16x32_bf16 v[34:37], v[164:167], v[180:183], v[34:37]
	v_mfma_f32_16x16x32_bf16 v[22:25], v[156:159], v[188:191], v[22:25]
	v_mfma_f32_16x16x32_bf16 v[18:21], v[164:167], v[188:191], v[18:21]
	v_mfma_f32_16x16x32_bf16 v[6:9], v[156:159], v[202:205], v[6:9]
	v_mfma_f32_16x16x32_bf16 v[2:5], v[164:167], v[202:205], v[2:5]
	v_mfma_f32_16x16x32_bf16 v[54:57], v[160:163], v[176:179], v[54:57]
	v_mfma_f32_16x16x32_bf16 v[50:53], v[168:171], v[176:179], v[50:53]
	v_mfma_f32_16x16x32_bf16 v[38:41], v[160:163], v[184:187], v[38:41]
	v_mfma_f32_16x16x32_bf16 v[34:37], v[168:171], v[184:187], v[34:37]
	v_mfma_f32_16x16x32_bf16 v[22:25], v[160:163], v[192:195], v[22:25]
	v_mfma_f32_16x16x32_bf16 v[18:21], v[168:171], v[192:195], v[18:21]
	v_mfma_f32_16x16x32_bf16 v[6:9], v[160:163], v[206:209], v[6:9]
	v_mfma_f32_16x16x32_bf16 v[2:5], v[168:171], v[206:209], v[2:5]
	s_setprio 0
	s_barrier
	s_add_i32 s29, s29, 2
	s_add_u32 vcc_lo, vcc_lo, 0x100
	s_addc_u32 vcc_hi, vcc_hi, 0
	s_add_u32 s73, s73, 0x100
	s_addc_u32 s28, s28, 0
	s_cmp_gt_u32 s29, 29
	s_cbranch_scc0 .LBB0_1062
	s_and_b64 vcc, exec, s[6:7]
	s_cbranch_vccz .LBB0_1065
	s_barrier
